# grid barrier: XCD leaders poll the arrival counter itself (one fabric hop less than waiting for the generation word), plus the early follower L1 invalidate
# speedup vs baseline: 1.0095x; 1.0036x over previous
.LBB0_668:
	s_or_b64 exec, exec, s[8:9]
	s_waitcnt vmcnt(0)
	v_readfirstlane_b32 s6, v2
	v_cvt_f32_u32_e32 v2, v0
	v_sub_u32_e32 v3, 0, v0
	v_add_u32_e32 v1, s6, v1
	v_readlane_b32 s6, v245, 13
	v_rcp_iflag_f32_e32 v2, v2
	v_readlane_b32 s7, v245, 14
	s_mov_b64 s[8:9], -1
	v_mul_f32_e32 v2, 0x4f7ffffe, v2
	v_cvt_u32_f32_e32 v2, v2
	v_mul_lo_u32 v3, v3, v2
	v_mul_hi_u32 v3, v2, v3
	v_add_u32_e32 v2, v2, v3
	v_mul_hi_u32 v2, v1, v2
	v_mul_lo_u32 v3, v2, v0
	v_sub_u32_e32 v3, v1, v3
	v_cmp_ge_u32_e32 vcc, v3, v0
	v_add_u32_e32 v4, 1, v2
	v_add_u32_e32 v1, 1, v1
	v_cndmask_b32_e32 v2, v2, v4, vcc
	v_sub_u32_e32 v4, v3, v0
	v_cndmask_b32_e32 v3, v3, v4, vcc
	v_cmp_ge_u32_e32 vcc, v3, v0
	v_add_u32_e32 v3, 1, v2
	s_nop 0
	v_cndmask_b32_e32 v2, v2, v3, vcc
	v_mul_lo_u32 v3, v0, v2
	v_add_u32_e32 v0, v3, v0
	v_cmp_ne_u32_e32 vcc, v1, v0
	v_mov_b32_e32 v4, v0
	v_mov_b64_e32 v[0:1], s[6:7]
	s_and_saveexec_b64 s[6:7], vcc
	s_cbranch_execz .LBB0_680
	v_readlane_b32 s8, v245, 11
	v_readlane_b32 s9, v245, 12
	s_mov_b64 s[10:11], 0
	s_nop 3
	global_load_dword v0, v137, s[8:9] sc1
	s_waitcnt vmcnt(0)
	v_cmp_lt_u32_e32 vcc, v0, v4
	s_and_saveexec_b64 s[8:9], vcc
	s_cbranch_execz .LBB0_679
	s_mov_b32 s20, 1
	s_branch .LBB0_672

.LBB0_676:
	v_readlane_b32 s14, v245, 11
	v_readlane_b32 s15, v245, 12
	s_add_i32 s20, s20, 1
	s_mov_b64 s[16:17], -1
	s_nop 2
	global_load_dword v0, v137, s[14:15] sc1
	s_waitcnt vmcnt(0)
	v_cmp_ge_u32_e32 vcc, v0, v4
	s_orn2_b64 s[14:15], vcc, exec
	s_branch .LBB0_671
